# post1: touch the per-token epilogue operands of both passes during the g-gate stage so the epilogue loads hit L2
# baseline (speedup 1.0000x reference)
.LBB0_1180:
	s_lshl_b32 s45, s44, 4
	s_mov_b32 s6, 0xffffde00
	s_mov_b32 s7, -1
	s_mov_b32 s24, 0x2200
	s_mov_b32 s25, 0
	v_lshlrev_b32_e32 v98, 1, v100
	global_load_dword v88, v[102:103], off
	global_load_dword v89, v[104:105], off
	v_or_b32_e32 v132, s45, v101
	v_mov_b64_e32 v[136:137], s[38:39]
	v_mad_i64_i32 v[136:137], s[0:1], v132, s35, v[136:137]
	v_lshl_add_u64 v[136:137], v[136:137], 0, v[98:99]
	v_lshl_add_u64 v[136:137], v[136:137], 0, s[20:21]
	v_lshl_add_u64 v[144:145], v[136:137], 0, s[6:7]
	v_lshl_add_u64 v[146:147], v[136:137], 0, s[24:25]
	global_load_ushort v148, v[136:137], off
	global_load_ushort v152, v[144:145], off
	global_load_ushort v156, v[146:147], off
	v_or_b32_e32 v133, s45, v120
	v_mov_b64_e32 v[138:139], s[38:39]
	v_mad_i64_i32 v[138:139], s[0:1], v133, s35, v[138:139]
	v_lshl_add_u64 v[138:139], v[138:139], 0, v[98:99]
	v_lshl_add_u64 v[138:139], v[138:139], 0, s[20:21]
	v_lshl_add_u64 v[144:145], v[138:139], 0, s[6:7]
	v_lshl_add_u64 v[146:147], v[138:139], 0, s[24:25]
	global_load_ushort v149, v[138:139], off
	global_load_ushort v153, v[144:145], off
	global_load_ushort v157, v[146:147], off
	v_or_b32_e32 v134, s45, v122
	v_mov_b64_e32 v[140:141], s[38:39]
	v_mad_i64_i32 v[140:141], s[0:1], v134, s35, v[140:141]
	v_lshl_add_u64 v[140:141], v[140:141], 0, v[98:99]
	v_lshl_add_u64 v[140:141], v[140:141], 0, s[20:21]
	v_lshl_add_u64 v[144:145], v[140:141], 0, s[6:7]
	v_lshl_add_u64 v[146:147], v[140:141], 0, s[24:25]
	global_load_ushort v150, v[140:141], off
	global_load_ushort v154, v[144:145], off
	global_load_ushort v158, v[146:147], off
	v_or_b32_e32 v135, s45, v123
	v_mov_b64_e32 v[142:143], s[38:39]
	v_mad_i64_i32 v[142:143], s[0:1], v135, s35, v[142:143]
	v_lshl_add_u64 v[142:143], v[142:143], 0, v[98:99]
	v_lshl_add_u64 v[142:143], v[142:143], 0, s[20:21]
	v_lshl_add_u64 v[144:145], v[142:143], 0, s[6:7]
	v_lshl_add_u64 v[146:147], v[142:143], 0, s[24:25]
	global_load_ushort v151, v[142:143], off
	global_load_ushort v155, v[144:145], off
	global_load_ushort v159, v[146:147], off
	v_lshlrev_b32_e32 v118, 1, v96
	v_mov_b32_e32 v119, 0
	v_mov_b32_e32 v91, 0
	v_mov_b32_e32 v93, 0
	v_add3_u32 v112, s45, v220, 0
	v_mov_b64_e32 v[114:115], s[38:39]
	v_mad_i64_i32 v[114:115], s[0:1], v112, s35, v[114:115]
	v_lshl_add_u64 v[114:115], v[114:115], 0, v[118:119]
	v_lshl_add_u64 v[114:115], v[114:115], 0, s[20:21]
	global_load_dwordx4 v[160:163], v[114:115], off
	global_load_dwordx4 v[160:163], v[114:115], off offset:1024
	global_load_dwordx4 v[160:163], v[114:115], off offset:2048
	v_lshl_add_u64 v[116:117], v[114:115], 0, s[6:7]
	global_load_dwordx4 v[160:163], v[116:117], off
	global_load_dwordx4 v[160:163], v[116:117], off offset:1024
	global_load_dwordx4 v[160:163], v[116:117], off offset:2048
	v_lshl_add_u64 v[116:117], v[114:115], 0, s[24:25]
	global_load_dwordx4 v[160:163], v[116:117], off
	global_load_dwordx4 v[160:163], v[116:117], off offset:1024
	global_load_dwordx4 v[160:163], v[116:117], off offset:2048
	v_lshlrev_b32_e32 v90, 10, v112
	v_lshl_add_u64 v[116:117], v[106:107], 0, v[90:91]
	global_load_dwordx4 v[160:163], v[116:117], off
	v_or_b32_e32 v92, v90, v108
	v_lshl_add_u64 v[116:117], v[92:93], 1, s[42:43]
	global_load_dwordx4 v[160:163], v[116:117], off
	v_or_b32_e32 v92, v90, v96
	v_lshl_add_u64 v[116:117], v[92:93], 1, s[26:27]
	global_load_dwordx4 v[160:163], v[116:117], off offset:1024
	v_add3_u32 v112, s45, v220, 8
	v_mov_b64_e32 v[114:115], s[38:39]
	v_mad_i64_i32 v[114:115], s[0:1], v112, s35, v[114:115]
	v_lshl_add_u64 v[114:115], v[114:115], 0, v[118:119]
	v_lshl_add_u64 v[114:115], v[114:115], 0, s[20:21]
	global_load_dwordx4 v[160:163], v[114:115], off
	global_load_dwordx4 v[160:163], v[114:115], off offset:1024
	global_load_dwordx4 v[160:163], v[114:115], off offset:2048
	v_lshl_add_u64 v[116:117], v[114:115], 0, s[6:7]
	global_load_dwordx4 v[160:163], v[116:117], off
	global_load_dwordx4 v[160:163], v[116:117], off offset:1024
	global_load_dwordx4 v[160:163], v[116:117], off offset:2048
	v_lshl_add_u64 v[116:117], v[114:115], 0, s[24:25]
	global_load_dwordx4 v[160:163], v[116:117], off
	global_load_dwordx4 v[160:163], v[116:117], off offset:1024
	global_load_dwordx4 v[160:163], v[116:117], off offset:2048
	v_lshlrev_b32_e32 v90, 10, v112
	v_lshl_add_u64 v[116:117], v[106:107], 0, v[90:91]
	global_load_dwordx4 v[160:163], v[116:117], off
	v_or_b32_e32 v92, v90, v108
	v_lshl_add_u64 v[116:117], v[92:93], 1, s[42:43]
	global_load_dwordx4 v[160:163], v[116:117], off
	v_or_b32_e32 v92, v90, v96
	v_lshl_add_u64 v[116:117], v[92:93], 1, s[26:27]
	global_load_dwordx4 v[160:163], v[116:117], off offset:1024
	s_waitcnt vmcnt(0)
	v_and_b32_e32 v90, v127, v132
	v_lshlrev_b32_e32 v91, 16, v148
	v_lshlrev_b32_e32 v92, 16, v152
	v_lshlrev_b32_e32 v93, 16, v156
	v_cmp_ne_u32_e32 vcc, 0, v90
	s_nop 1
	v_cndmask_b32_e32 v92, 0, v92, vcc
	v_cmp_ne_u32_e32 vcc, s40, v90
	s_nop 1
	v_cndmask_b32_e32 v93, 0, v93, vcc
	v_sub_f32_e32 v92, v92, v91
	v_sub_f32_e32 v93, v93, v91
	v_mul_f32_e32 v92, v92, v88
	v_mul_f32_e32 v93, v93, v89
	v_add_f32_e32 v92, v92, v91
	v_add_f32_e32 v92, v92, v93
	v_mul_f32_e32 v92, 0xbfb8aa3b, v92
	v_exp_f32_e32 v92, v92
	s_nop 0
	v_add_f32_e32 v95, 1.0, v92
	v_div_scale_f32 v93, s[0:1], v95, v95, 1.0
	v_rcp_f32_e32 v94, v93
	v_div_scale_f32 v112, vcc, 1.0, v95, 1.0
	v_fma_f32 v113, -v93, v94, 1.0
	v_fmac_f32_e32 v94, v113, v94
	v_mul_f32_e32 v113, v112, v94
	v_fma_f32 v114, -v93, v113, v112
	v_fmac_f32_e32 v113, v114, v94
	v_fma_f32 v93, -v93, v113, v112
	v_div_fmas_f32 v112, v93, v94, v113
	v_div_fixup_f32 v92, v112, v95, 1.0
	ds_write_b32 v109, v92
	v_and_b32_e32 v90, v127, v133
	v_lshlrev_b32_e32 v91, 16, v149
	v_lshlrev_b32_e32 v92, 16, v153
	v_lshlrev_b32_e32 v93, 16, v157
	v_cmp_ne_u32_e32 vcc, 0, v90
	s_nop 1
	v_cndmask_b32_e32 v92, 0, v92, vcc
	v_cmp_ne_u32_e32 vcc, s40, v90
	s_nop 1
	v_cndmask_b32_e32 v93, 0, v93, vcc
	v_sub_f32_e32 v92, v92, v91
	v_sub_f32_e32 v93, v93, v91
	v_mul_f32_e32 v92, v92, v88
	v_mul_f32_e32 v93, v93, v89
	v_add_f32_e32 v92, v92, v91
	v_add_f32_e32 v92, v92, v93
	v_mul_f32_e32 v92, 0xbfb8aa3b, v92
	v_exp_f32_e32 v92, v92
	s_nop 0
	v_add_f32_e32 v95, 1.0, v92
	v_div_scale_f32 v93, s[0:1], v95, v95, 1.0
	v_rcp_f32_e32 v94, v93
	v_div_scale_f32 v112, vcc, 1.0, v95, 1.0
	v_fma_f32 v113, -v93, v94, 1.0
	v_fmac_f32_e32 v94, v113, v94
	v_mul_f32_e32 v113, v112, v94
	v_fma_f32 v114, -v93, v113, v112
	v_fmac_f32_e32 v113, v114, v94
	v_fma_f32 v93, -v93, v113, v112
	v_div_fmas_f32 v112, v93, v94, v113
	v_div_fixup_f32 v92, v112, v95, 1.0
	ds_write_b32 v121, v92
	v_and_b32_e32 v90, v127, v134
	v_lshlrev_b32_e32 v91, 16, v150
	v_lshlrev_b32_e32 v92, 16, v154
	v_lshlrev_b32_e32 v93, 16, v158
	v_cmp_ne_u32_e32 vcc, 0, v90
	s_nop 1
	v_cndmask_b32_e32 v92, 0, v92, vcc
	v_cmp_ne_u32_e32 vcc, s40, v90
	s_nop 1
	v_cndmask_b32_e32 v93, 0, v93, vcc
	v_sub_f32_e32 v92, v92, v91
	v_sub_f32_e32 v93, v93, v91
	v_mul_f32_e32 v92, v92, v88
	v_mul_f32_e32 v93, v93, v89
	v_add_f32_e32 v92, v92, v91
	v_add_f32_e32 v92, v92, v93
	v_mul_f32_e32 v92, 0xbfb8aa3b, v92
	v_exp_f32_e32 v92, v92
	s_nop 0
	v_add_f32_e32 v95, 1.0, v92
	v_div_scale_f32 v93, s[0:1], v95, v95, 1.0
	v_rcp_f32_e32 v94, v93
	v_div_scale_f32 v112, vcc, 1.0, v95, 1.0
	v_fma_f32 v113, -v93, v94, 1.0
	v_fmac_f32_e32 v94, v113, v94
	v_mul_f32_e32 v113, v112, v94
	v_fma_f32 v114, -v93, v113, v112
	v_fmac_f32_e32 v113, v114, v94
	v_fma_f32 v93, -v93, v113, v112
	v_div_fmas_f32 v112, v93, v94, v113
	v_div_fixup_f32 v92, v112, v95, 1.0
	ds_write_b32 v109, v92 offset:32
	v_and_b32_e32 v90, v127, v135
	v_lshlrev_b32_e32 v91, 16, v151
	v_lshlrev_b32_e32 v92, 16, v155
	v_lshlrev_b32_e32 v93, 16, v159
	v_cmp_ne_u32_e32 vcc, 0, v90
	s_nop 1
	v_cndmask_b32_e32 v92, 0, v92, vcc
	v_cmp_ne_u32_e32 vcc, s40, v90
	s_nop 1
	v_cndmask_b32_e32 v93, 0, v93, vcc
	v_sub_f32_e32 v92, v92, v91
	v_sub_f32_e32 v93, v93, v91
	v_mul_f32_e32 v92, v92, v88
	v_mul_f32_e32 v93, v93, v89
	v_add_f32_e32 v92, v92, v91
	v_add_f32_e32 v92, v92, v93
	v_mul_f32_e32 v92, 0xbfb8aa3b, v92
	v_exp_f32_e32 v92, v92
	s_nop 0
	v_add_f32_e32 v95, 1.0, v92
	v_div_scale_f32 v93, s[0:1], v95, v95, 1.0
	v_rcp_f32_e32 v94, v93
	v_div_scale_f32 v112, vcc, 1.0, v95, 1.0
	v_fma_f32 v113, -v93, v94, 1.0
	v_fmac_f32_e32 v94, v113, v94
	v_mul_f32_e32 v113, v112, v94
	v_fma_f32 v114, -v93, v113, v112
	v_fmac_f32_e32 v113, v114, v94
	v_fma_f32 v93, -v93, v113, v112
	v_div_fmas_f32 v112, v93, v94, v113
	v_div_fixup_f32 v92, v112, v95, 1.0
	ds_write_b32 v124, v92
	v_mov_b32_e32 v88, 0
	v_mov_b32_e32 v89, 0
	v_mov_b32_e32 v90, 0
	v_mov_b32_e32 v91, 0
	v_mov_b32_e32 v92, 0
	v_mov_b32_e32 v93, 0
	v_mov_b32_e32 v94, 0
	v_mov_b32_e32 v95, 0
	v_mov_b32_e32 v112, 0
	v_mov_b32_e32 v113, 0
	v_mov_b32_e32 v114, 0
	v_mov_b32_e32 v115, 0
	v_mov_b32_e32 v116, 0
	v_mov_b32_e32 v117, 0
	v_mov_b32_e32 v118, 0
	v_mov_b32_e32 v119, 0
	s_mov_b32 s6, 0
	s_mov_b64 s[0:1], 0
	s_waitcnt lgkmcnt(0)
	s_barrier
	v_readlane_b32 s0, v255, 33
	v_readlane_b32 s1, v255, 34
	v_and_b32_e32 v151, 63, v164
	v_lshrrev_b32_e32 v152, 6, v164
	v_lshlrev_b32_e32 v148, 2, v151
	v_lshrrev_b32_e32 v153, 4, v151
	v_and_b32_e32 v154, 15, v151
	v_lshlrev_b32_e32 v149, 11, v153
	v_lshl_add_u32 v149, v152, 8, v149
	v_lshl_add_u32 v149, v154, 4, v149
	v_lshlrev_b32_e32 v150, 13, v153
	v_lshl_add_u32 v150, v152, 8, v150
	v_lshl_add_u32 v150, v154, 4, v150
	v_add_u32_e32 v150, 0x2000, v150
	global_load_dwordx4 v[136:139], v149, s[0:1]
	v_add_u32_e32 v149, 0x2000, v149
	ds_read_b32 v132, v148 offset:0
	global_load_dwordx4 v[140:143], v149, s[0:1]
	v_add_u32_e32 v149, 0x2000, v149
	ds_read_b32 v133, v148 offset:256
	global_load_dwordx4 v[144:147], v149, s[0:1]
	v_add_u32_e32 v149, 0x2000, v149
	ds_read_b32 v134, v148 offset:512
	s_waitcnt vmcnt(2) lgkmcnt(2)
	v_mfma_f32_16x16x4_f32 v[88:91], v132, v136, v[88:91]
	v_mfma_f32_16x16x4_f32 v[92:95], v132, v137, v[92:95]
	v_mfma_f32_16x16x4_f32 v[112:115], v132, v138, v[112:115]
	v_mfma_f32_16x16x4_f32 v[116:119], v132, v139, v[116:119]
	global_load_dwordx4 v[136:139], v149, s[0:1]
	v_add_u32_e32 v149, 0x2000, v149
	ds_read_b32 v132, v148 offset:768
	s_waitcnt vmcnt(2) lgkmcnt(2)
	v_mfma_f32_16x16x4_f32 v[88:91], v133, v140, v[88:91]
	v_mfma_f32_16x16x4_f32 v[92:95], v133, v141, v[92:95]
	v_mfma_f32_16x16x4_f32 v[112:115], v133, v142, v[112:115]
	v_mfma_f32_16x16x4_f32 v[116:119], v133, v143, v[116:119]
	global_load_dwordx4 v[140:143], v149, s[0:1]
	v_add_u32_e32 v149, 0x2000, v149
	ds_read_b32 v133, v148 offset:1024
	s_waitcnt vmcnt(2) lgkmcnt(2)
	v_mfma_f32_16x16x4_f32 v[88:91], v134, v144, v[88:91]
	v_mfma_f32_16x16x4_f32 v[92:95], v134, v145, v[92:95]
	v_mfma_f32_16x16x4_f32 v[112:115], v134, v146, v[112:115]
	v_mfma_f32_16x16x4_f32 v[116:119], v134, v147, v[116:119]
	global_load_dwordx4 v[144:147], v149, s[0:1]
	v_add_u32_e32 v149, 0x2000, v149
	ds_read_b32 v134, v148 offset:1280
	s_waitcnt vmcnt(2) lgkmcnt(2)
	v_mfma_f32_16x16x4_f32 v[88:91], v132, v136, v[88:91]
	v_mfma_f32_16x16x4_f32 v[92:95], v132, v137, v[92:95]
	v_mfma_f32_16x16x4_f32 v[112:115], v132, v138, v[112:115]
	v_mfma_f32_16x16x4_f32 v[116:119], v132, v139, v[116:119]
	global_load_dwordx4 v[136:139], v149, s[0:1]
	v_add_u32_e32 v149, 0x2000, v149
	ds_read_b32 v132, v148 offset:1536
	s_waitcnt vmcnt(2) lgkmcnt(2)
	v_mfma_f32_16x16x4_f32 v[88:91], v133, v140, v[88:91]
	v_mfma_f32_16x16x4_f32 v[92:95], v133, v141, v[92:95]
	v_mfma_f32_16x16x4_f32 v[112:115], v133, v142, v[112:115]
	v_mfma_f32_16x16x4_f32 v[116:119], v133, v143, v[116:119]
	global_load_dwordx4 v[140:143], v149, s[0:1]
	v_add_u32_e32 v149, 0x2000, v149
	ds_read_b32 v133, v148 offset:1792
	s_waitcnt vmcnt(2) lgkmcnt(2)
	v_mfma_f32_16x16x4_f32 v[88:91], v134, v144, v[88:91]
	v_mfma_f32_16x16x4_f32 v[92:95], v134, v145, v[92:95]
	v_mfma_f32_16x16x4_f32 v[112:115], v134, v146, v[112:115]
	v_mfma_f32_16x16x4_f32 v[116:119], v134, v147, v[116:119]
	global_load_dwordx4 v[144:147], v149, s[0:1]
	v_add_u32_e32 v149, 0x2000, v149
	ds_read_b32 v134, v148 offset:2048
	s_waitcnt vmcnt(2) lgkmcnt(2)
	v_mfma_f32_16x16x4_f32 v[88:91], v132, v136, v[88:91]
	v_mfma_f32_16x16x4_f32 v[92:95], v132, v137, v[92:95]
	v_mfma_f32_16x16x4_f32 v[112:115], v132, v138, v[112:115]
	v_mfma_f32_16x16x4_f32 v[116:119], v132, v139, v[116:119]
	global_load_dwordx4 v[136:139], v149, s[0:1]
	v_add_u32_e32 v149, 0x2000, v149
	ds_read_b32 v132, v148 offset:2304
	s_waitcnt vmcnt(2) lgkmcnt(2)
	v_mfma_f32_16x16x4_f32 v[88:91], v133, v140, v[88:91]
	v_mfma_f32_16x16x4_f32 v[92:95], v133, v141, v[92:95]
	v_mfma_f32_16x16x4_f32 v[112:115], v133, v142, v[112:115]
	v_mfma_f32_16x16x4_f32 v[116:119], v133, v143, v[116:119]
	global_load_dwordx4 v[140:143], v149, s[0:1]
	v_add_u32_e32 v149, 0x2000, v149
	ds_read_b32 v133, v148 offset:2560
	s_waitcnt vmcnt(2) lgkmcnt(2)
	v_mfma_f32_16x16x4_f32 v[88:91], v134, v144, v[88:91]
	v_mfma_f32_16x16x4_f32 v[92:95], v134, v145, v[92:95]
	v_mfma_f32_16x16x4_f32 v[112:115], v134, v146, v[112:115]
	v_mfma_f32_16x16x4_f32 v[116:119], v134, v147, v[116:119]
	global_load_dwordx4 v[144:147], v149, s[0:1]
	v_add_u32_e32 v149, 0x2000, v149
	ds_read_b32 v134, v148 offset:2816
	s_waitcnt vmcnt(2) lgkmcnt(2)
	v_mfma_f32_16x16x4_f32 v[88:91], v132, v136, v[88:91]
	v_mfma_f32_16x16x4_f32 v[92:95], v132, v137, v[92:95]
	v_mfma_f32_16x16x4_f32 v[112:115], v132, v138, v[112:115]
	v_mfma_f32_16x16x4_f32 v[116:119], v132, v139, v[116:119]
	global_load_dwordx4 v[136:139], v149, s[0:1]
	v_add_u32_e32 v149, 0x2000, v149
	ds_read_b32 v132, v148 offset:3072
	s_waitcnt vmcnt(2) lgkmcnt(2)
	v_mfma_f32_16x16x4_f32 v[88:91], v133, v140, v[88:91]
	v_mfma_f32_16x16x4_f32 v[92:95], v133, v141, v[92:95]
	v_mfma_f32_16x16x4_f32 v[112:115], v133, v142, v[112:115]
	v_mfma_f32_16x16x4_f32 v[116:119], v133, v143, v[116:119]
	global_load_dwordx4 v[140:143], v149, s[0:1]
	v_add_u32_e32 v149, 0x2000, v149
	ds_read_b32 v133, v148 offset:3328
	s_waitcnt vmcnt(2) lgkmcnt(2)
	v_mfma_f32_16x16x4_f32 v[88:91], v134, v144, v[88:91]
	v_mfma_f32_16x16x4_f32 v[92:95], v134, v145, v[92:95]
	v_mfma_f32_16x16x4_f32 v[112:115], v134, v146, v[112:115]
	v_mfma_f32_16x16x4_f32 v[116:119], v134, v147, v[116:119]
	global_load_dwordx4 v[144:147], v149, s[0:1]
	v_add_u32_e32 v149, 0x2000, v149
	ds_read_b32 v134, v148 offset:3584
	s_waitcnt vmcnt(2) lgkmcnt(2)
	v_mfma_f32_16x16x4_f32 v[88:91], v132, v136, v[88:91]
	v_mfma_f32_16x16x4_f32 v[92:95], v132, v137, v[92:95]
	v_mfma_f32_16x16x4_f32 v[112:115], v132, v138, v[112:115]
	v_mfma_f32_16x16x4_f32 v[116:119], v132, v139, v[116:119]
	global_load_dwordx4 v[136:139], v149, s[0:1]
	v_add_u32_e32 v149, 0x2000, v149
	ds_read_b32 v132, v148 offset:3840
	s_waitcnt vmcnt(2) lgkmcnt(2)
	v_mfma_f32_16x16x4_f32 v[88:91], v133, v140, v[88:91]
	v_mfma_f32_16x16x4_f32 v[92:95], v133, v141, v[92:95]
	v_mfma_f32_16x16x4_f32 v[112:115], v133, v142, v[112:115]
	v_mfma_f32_16x16x4_f32 v[116:119], v133, v143, v[116:119]
	global_load_dwordx4 v[140:143], v149, s[0:1]
	v_add_u32_e32 v149, 0x2000, v149
	ds_read_b32 v133, v148 offset:4096
	s_waitcnt vmcnt(2) lgkmcnt(2)
	v_mfma_f32_16x16x4_f32 v[88:91], v134, v144, v[88:91]
	v_mfma_f32_16x16x4_f32 v[92:95], v134, v145, v[92:95]
	v_mfma_f32_16x16x4_f32 v[112:115], v134, v146, v[112:115]
	v_mfma_f32_16x16x4_f32 v[116:119], v134, v147, v[116:119]
	global_load_dwordx4 v[144:147], v149, s[0:1]
	v_add_u32_e32 v149, 0x2000, v149
	ds_read_b32 v134, v148 offset:4352
	s_waitcnt vmcnt(2) lgkmcnt(2)
	v_mfma_f32_16x16x4_f32 v[88:91], v132, v136, v[88:91]
	v_mfma_f32_16x16x4_f32 v[92:95], v132, v137, v[92:95]
	v_mfma_f32_16x16x4_f32 v[112:115], v132, v138, v[112:115]
	v_mfma_f32_16x16x4_f32 v[116:119], v132, v139, v[116:119]
	global_load_dwordx4 v[136:139], v149, s[0:1]
	v_add_u32_e32 v149, 0x2000, v149
	ds_read_b32 v132, v148 offset:4608
	s_waitcnt vmcnt(2) lgkmcnt(2)
	v_mfma_f32_16x16x4_f32 v[88:91], v133, v140, v[88:91]
	v_mfma_f32_16x16x4_f32 v[92:95], v133, v141, v[92:95]
	v_mfma_f32_16x16x4_f32 v[112:115], v133, v142, v[112:115]
	v_mfma_f32_16x16x4_f32 v[116:119], v133, v143, v[116:119]
	global_load_dwordx4 v[140:143], v149, s[0:1]
	v_add_u32_e32 v149, 0x2000, v149
	ds_read_b32 v133, v148 offset:4864
	s_waitcnt vmcnt(2) lgkmcnt(2)
	v_mfma_f32_16x16x4_f32 v[88:91], v134, v144, v[88:91]
	v_mfma_f32_16x16x4_f32 v[92:95], v134, v145, v[92:95]
	v_mfma_f32_16x16x4_f32 v[112:115], v134, v146, v[112:115]
	v_mfma_f32_16x16x4_f32 v[116:119], v134, v147, v[116:119]
	global_load_dwordx4 v[144:147], v149, s[0:1]
	v_add_u32_e32 v149, 0x2000, v149
	ds_read_b32 v134, v148 offset:5120
	s_waitcnt vmcnt(2) lgkmcnt(2)
	v_mfma_f32_16x16x4_f32 v[88:91], v132, v136, v[88:91]
	v_mfma_f32_16x16x4_f32 v[92:95], v132, v137, v[92:95]
	v_mfma_f32_16x16x4_f32 v[112:115], v132, v138, v[112:115]
	v_mfma_f32_16x16x4_f32 v[116:119], v132, v139, v[116:119]
	global_load_dwordx4 v[136:139], v149, s[0:1]
	v_add_u32_e32 v149, 0x2000, v149
	ds_read_b32 v132, v148 offset:5376
	s_waitcnt vmcnt(2) lgkmcnt(2)
	v_mfma_f32_16x16x4_f32 v[88:91], v133, v140, v[88:91]
	v_mfma_f32_16x16x4_f32 v[92:95], v133, v141, v[92:95]
	v_mfma_f32_16x16x4_f32 v[112:115], v133, v142, v[112:115]
	v_mfma_f32_16x16x4_f32 v[116:119], v133, v143, v[116:119]
	global_load_dwordx4 v[140:143], v149, s[0:1]
	v_add_u32_e32 v149, 0x2000, v149
	ds_read_b32 v133, v148 offset:5632
	s_waitcnt vmcnt(2) lgkmcnt(2)
	v_mfma_f32_16x16x4_f32 v[88:91], v134, v144, v[88:91]
	v_mfma_f32_16x16x4_f32 v[92:95], v134, v145, v[92:95]
	v_mfma_f32_16x16x4_f32 v[112:115], v134, v146, v[112:115]
	v_mfma_f32_16x16x4_f32 v[116:119], v134, v147, v[116:119]
	global_load_dwordx4 v[144:147], v149, s[0:1]
	v_add_u32_e32 v149, 0x2000, v149
	ds_read_b32 v134, v148 offset:5888
	s_waitcnt vmcnt(2) lgkmcnt(2)
	v_mfma_f32_16x16x4_f32 v[88:91], v132, v136, v[88:91]
	v_mfma_f32_16x16x4_f32 v[92:95], v132, v137, v[92:95]
	v_mfma_f32_16x16x4_f32 v[112:115], v132, v138, v[112:115]
	v_mfma_f32_16x16x4_f32 v[116:119], v132, v139, v[116:119]
	global_load_dwordx4 v[136:139], v149, s[0:1]
	v_add_u32_e32 v149, 0x2000, v149
	ds_read_b32 v132, v148 offset:6144
	s_waitcnt vmcnt(2) lgkmcnt(2)
	v_mfma_f32_16x16x4_f32 v[88:91], v133, v140, v[88:91]
	v_mfma_f32_16x16x4_f32 v[92:95], v133, v141, v[92:95]
	v_mfma_f32_16x16x4_f32 v[112:115], v133, v142, v[112:115]
	v_mfma_f32_16x16x4_f32 v[116:119], v133, v143, v[116:119]
	global_load_dwordx4 v[140:143], v149, s[0:1]
	v_add_u32_e32 v149, 0x2000, v149
	ds_read_b32 v133, v148 offset:6400
	s_waitcnt vmcnt(2) lgkmcnt(2)
	v_mfma_f32_16x16x4_f32 v[88:91], v134, v144, v[88:91]
	v_mfma_f32_16x16x4_f32 v[92:95], v134, v145, v[92:95]
	v_mfma_f32_16x16x4_f32 v[112:115], v134, v146, v[112:115]
	v_mfma_f32_16x16x4_f32 v[116:119], v134, v147, v[116:119]
	global_load_dwordx4 v[144:147], v149, s[0:1]
	v_add_u32_e32 v149, 0x2000, v149
	ds_read_b32 v134, v148 offset:6656
	s_waitcnt vmcnt(2) lgkmcnt(2)
	v_mfma_f32_16x16x4_f32 v[88:91], v132, v136, v[88:91]
	v_mfma_f32_16x16x4_f32 v[92:95], v132, v137, v[92:95]
	v_mfma_f32_16x16x4_f32 v[112:115], v132, v138, v[112:115]
	v_mfma_f32_16x16x4_f32 v[116:119], v132, v139, v[116:119]
	global_load_dwordx4 v[136:139], v149, s[0:1]
	v_add_u32_e32 v149, 0x2000, v149
	ds_read_b32 v132, v148 offset:6912
	s_waitcnt vmcnt(2) lgkmcnt(2)
	v_mfma_f32_16x16x4_f32 v[88:91], v133, v140, v[88:91]
	v_mfma_f32_16x16x4_f32 v[92:95], v133, v141, v[92:95]
	v_mfma_f32_16x16x4_f32 v[112:115], v133, v142, v[112:115]
	v_mfma_f32_16x16x4_f32 v[116:119], v133, v143, v[116:119]
	global_load_dwordx4 v[140:143], v149, s[0:1]
	v_add_u32_e32 v149, 0x2000, v149
	ds_read_b32 v133, v148 offset:7168
	s_waitcnt vmcnt(2) lgkmcnt(2)
	v_mfma_f32_16x16x4_f32 v[88:91], v134, v144, v[88:91]
	v_mfma_f32_16x16x4_f32 v[92:95], v134, v145, v[92:95]
	v_mfma_f32_16x16x4_f32 v[112:115], v134, v146, v[112:115]
	v_mfma_f32_16x16x4_f32 v[116:119], v134, v147, v[116:119]
	global_load_dwordx4 v[144:147], v149, s[0:1]
	v_add_u32_e32 v149, 0x2000, v149
	ds_read_b32 v134, v148 offset:7424
	s_waitcnt vmcnt(2) lgkmcnt(2)
	v_mfma_f32_16x16x4_f32 v[88:91], v132, v136, v[88:91]
	v_mfma_f32_16x16x4_f32 v[92:95], v132, v137, v[92:95]
	v_mfma_f32_16x16x4_f32 v[112:115], v132, v138, v[112:115]
	v_mfma_f32_16x16x4_f32 v[116:119], v132, v139, v[116:119]
	global_load_dwordx4 v[136:139], v149, s[0:1]
	v_add_u32_e32 v149, 0x2000, v149
	ds_read_b32 v132, v148 offset:7680
	s_waitcnt vmcnt(2) lgkmcnt(2)
	v_mfma_f32_16x16x4_f32 v[88:91], v133, v140, v[88:91]
	v_mfma_f32_16x16x4_f32 v[92:95], v133, v141, v[92:95]
	v_mfma_f32_16x16x4_f32 v[112:115], v133, v142, v[112:115]
	v_mfma_f32_16x16x4_f32 v[116:119], v133, v143, v[116:119]
	global_load_dwordx4 v[140:143], v149, s[0:1]
	v_add_u32_e32 v149, 0x2000, v149
	ds_read_b32 v133, v148 offset:7936
	s_waitcnt vmcnt(2) lgkmcnt(2)
	v_mfma_f32_16x16x4_f32 v[88:91], v134, v144, v[88:91]
	v_mfma_f32_16x16x4_f32 v[92:95], v134, v145, v[92:95]
	v_mfma_f32_16x16x4_f32 v[112:115], v134, v146, v[112:115]
	v_mfma_f32_16x16x4_f32 v[116:119], v134, v147, v[116:119]
	s_waitcnt vmcnt(1) lgkmcnt(1)
	v_mfma_f32_16x16x4_f32 v[88:91], v132, v136, v[88:91]
	v_mfma_f32_16x16x4_f32 v[92:95], v132, v137, v[92:95]
	v_mfma_f32_16x16x4_f32 v[112:115], v132, v138, v[112:115]
	v_mfma_f32_16x16x4_f32 v[116:119], v132, v139, v[116:119]
	s_waitcnt vmcnt(0) lgkmcnt(0)
	v_mfma_f32_16x16x4_f32 v[88:91], v133, v140, v[88:91]
	v_mfma_f32_16x16x4_f32 v[92:95], v133, v141, v[92:95]
	v_mfma_f32_16x16x4_f32 v[112:115], v133, v142, v[112:115]
	v_mfma_f32_16x16x4_f32 v[116:119], v133, v143, v[116:119]
	s_nop 15
	s_nop 3
	s_mov_b32 s46, 0
	s_mov_b64 s[24:25], -1
	ds_write_b32 v150, v88 offset:0
	ds_write_b32 v150, v89 offset:2048
	ds_write_b32 v150, v90 offset:4096
	ds_write_b32 v150, v91 offset:6144
	ds_write_b32 v150, v92 offset:4
	ds_write_b32 v150, v93 offset:2052
	ds_write_b32 v150, v94 offset:4100
	ds_write_b32 v150, v95 offset:6148
	ds_write_b32 v150, v112 offset:8
	ds_write_b32 v150, v113 offset:2056
	ds_write_b32 v150, v114 offset:4104
	ds_write_b32 v150, v115 offset:6152
	ds_write_b32 v150, v116 offset:12
	ds_write_b32 v150, v117 offset:2060
	ds_write_b32 v150, v118 offset:4108
	ds_write_b32 v150, v119 offset:6156
	s_waitcnt lgkmcnt(0)
	s_barrier
